# ATTB fast-path row-max tree: 8 max3 ops instead of 20 (drop canonicalizing self-max)
# speedup vs baseline: 1.0261x; 1.0012x over previous
; template <int MODE>
; __device__ __forceinline__ void attn_pass(LAS unsigned char* lds, const bf16_t* base, int gk, int q0, const float* relb_b, const unsigned* selrow, f32x4 (&o)[2][4]) {
;     ...
;             if (fast) {
;                 float mx = fmaxf(fmaxf(s[qt][0][0], s[qt][0][1]), fmaxf(s[qt][0][2], s[qt][0][3]));
; #pragma unroll
;                 for (int nt = 1; nt < 4; ++nt) mx = fmaxf(mx, fmaxf(fmaxf(s[qt][nt][0], s[qt][nt][1]), fmaxf(s[qt][nt][2], s[qt][nt][3])));
;                 mx = fmaxf(mx, __shfl_xor(mx, 16)); mx = fmaxf(mx, __shfl_xor(mx, 32));
;                 const float mxl = selb ? (mx * C1 + bias_far) : -1e30f;
;                 mnew = fmaxf(mrun[qt], mxl); alpha = __builtin_amdgcn_exp2f(mrun[qt] - mnew);
;                 const float c1 = selb ? C1 : 0.f, c2 = selb ? (bias_far - mnew) : -1e30f;
; #pragma unroll
;                 for (int nt = 0; nt < 4; ++nt)
; #pragma unroll
;                     for (int j = 0; j < 4; ++j) s[qt][nt][j] = __builtin_amdgcn_exp2f(s[qt][nt][j] * c1 + c2);
.LBB0_108:
	v_max3_f32 v2, v143, v142, v141
	v_max3_f32 v2, v2, v140, v139
	v_max3_f32 v2, v2, v138, v137
	v_max3_f32 v2, v2, v136, v135
	v_max3_f32 v2, v2, v134, v133
	v_max3_f32 v2, v2, v132, v131
	v_max3_f32 v2, v2, v130, v129
	v_max_f32_e32 v2, v2, v128
	v_mov_b32_e32 v3, v2
	s_waitcnt lgkmcnt(0)
	s_nop 1
	v_permlane16_swap_b32_e32 v2, v3
	s_nop 0
	v_max_f32_e32 v2, v2, v3
	v_mov_b32_e32 v3, v2
	s_nop 1
	v_permlane32_swap_b32_e32 v2, v3
	s_nop 0
	v_max_f32_e32 v2, v2, v3
	v_fmamk_f32 v2, v2, 0x3e38aa3b, v150
	v_cndmask_b32_e64 v2, v2, v226, s[0:1]
	v_max_f32_e32 v3, v157, v157
	v_max_f32_e32 v3, v3, v2
	v_sub_f32_e32 v112, v150, v3
	v_cndmask_b32_e64 v2, v227, 0, s[0:1]
	v_cndmask_b32_e64 v156, v112, v226, s[0:1]
	v_fma_f32 v112, v2, v140, v156
	v_fma_f32 v113, v2, v141, v156
	v_fma_f32 v114, v2, v142, v156
	v_fma_f32 v115, v2, v143, v156
	v_fma_f32 v116, v2, v136, v156
	v_fma_f32 v117, v2, v137, v156
	v_fma_f32 v118, v2, v138, v156
	v_fma_f32 v119, v2, v139, v156
	v_fma_f32 v120, v2, v132, v156
	v_fma_f32 v121, v2, v133, v156
	v_fma_f32 v122, v2, v134, v156
	v_fma_f32 v123, v2, v135, v156
	v_fma_f32 v124, v2, v128, v156
	v_fma_f32 v125, v2, v129, v156
	v_fma_f32 v126, v2, v130, v156
	v_exp_f32_e32 v112, v112
	v_exp_f32_e32 v113, v113
	v_exp_f32_e32 v114, v114
	v_exp_f32_e32 v115, v115
	v_exp_f32_e32 v116, v116
	v_exp_f32_e32 v117, v117
	v_exp_f32_e32 v118, v118
	v_exp_f32_e32 v119, v119
	v_exp_f32_e32 v120, v120
	v_exp_f32_e32 v121, v121
	v_exp_f32_e32 v122, v122
	v_exp_f32_e32 v123, v123
	v_exp_f32_e32 v124, v124
	v_exp_f32_e32 v125, v125
	v_exp_f32_e32 v126, v126
	v_fmac_f32_e32 v156, v2, v131
	v_sub_f32_e32 v2, v157, v3
	v_exp_f32_e32 v2, v2
	v_cmp_gt_f32_e32 vcc, v3, v157
	s_cbranch_vccnz .LBB0_66
	s_branch .LBB0_67

; template <int MODE>
; __device__ __forceinline__ void attn_pass(LAS unsigned char* lds, const bf16_t* base, int gk, int q0, const float* relb_b, const unsigned* selrow, f32x4 (&o)[2][4]) {
;     ...
;             if (fast) {
;                 float mx = fmaxf(fmaxf(s[qt][0][0], s[qt][0][1]), fmaxf(s[qt][0][2], s[qt][0][3]));
; #pragma unroll
;                 for (int nt = 1; nt < 4; ++nt) mx = fmaxf(mx, fmaxf(fmaxf(s[qt][nt][0], s[qt][nt][1]), fmaxf(s[qt][nt][2], s[qt][nt][3])));
;                 mx = fmaxf(mx, __shfl_xor(mx, 16)); mx = fmaxf(mx, __shfl_xor(mx, 32));
;                 const float mxl = selb ? (mx * C1 + bias_far) : -1e30f;
;                 mnew = fmaxf(mrun[qt], mxl); alpha = __builtin_amdgcn_exp2f(mrun[qt] - mnew);
;                 const float c1 = selb ? C1 : 0.f, c2 = selb ? (bias_far - mnew) : -1e30f;
; #pragma unroll
;                 for (int nt = 0; nt < 4; ++nt)
; #pragma unroll
;                     for (int j = 0; j < 4; ++j) s[qt][nt][j] = __builtin_amdgcn_exp2f(s[qt][nt][j] * c1 + c2);
.LBB0_142:
	v_max3_f32 v127, v111, v110, v109
	v_max3_f32 v127, v127, v108, v107
	v_max3_f32 v127, v127, v106, v105
	v_max3_f32 v127, v127, v104, v103
	v_max3_f32 v127, v127, v102, v101
	v_max3_f32 v127, v127, v100, v99
	v_max3_f32 v127, v127, v98, v97
	v_max_f32_e32 v127, v127, v96
	v_mov_b32_e32 v128, v127
	v_cndmask_b32_e64 v143, v227, 0, s[0:1]
	s_waitcnt lgkmcnt(0)
	s_nop 1
	v_permlane16_swap_b32_e32 v127, v128
	s_nop 0
	v_max_f32_e32 v127, v127, v128
	v_mov_b32_e32 v128, v127
	s_nop 1
	v_permlane32_swap_b32_e32 v127, v128
	s_nop 0
	v_max_f32_e32 v127, v127, v128
	v_fmamk_f32 v127, v127, 0x3e38aa3b, v150
	v_cndmask_b32_e64 v127, v127, v226, s[0:1]
	v_max_f32_e32 v128, v155, v155
	v_max_f32_e32 v127, v128, v127
	v_sub_f32_e32 v128, v150, v127
	v_cndmask_b32_e64 v157, v128, v226, s[0:1]
	v_fma_f32 v108, v143, v108, v157
	v_fma_f32 v104, v143, v104, v157
	v_fma_f32 v100, v143, v100, v157
	v_exp_f32_e32 v128, v108
	v_fma_f32 v108, v143, v109, v157
	v_exp_f32_e32 v132, v104
	v_fma_f32 v104, v143, v105, v157
	v_exp_f32_e32 v136, v100
	v_fma_f32 v100, v143, v101, v157
	v_fma_f32 v96, v143, v96, v157
	v_exp_f32_e32 v129, v108
	v_fma_f32 v108, v143, v110, v157
	v_exp_f32_e32 v133, v104
	v_fma_f32 v104, v143, v106, v157
	v_exp_f32_e32 v137, v100
	v_fma_f32 v100, v143, v102, v157
	v_exp_f32_e32 v140, v96
	v_fma_f32 v96, v143, v97, v157
	v_exp_f32_e32 v130, v108
	v_fma_f32 v108, v143, v111, v157
	v_exp_f32_e32 v134, v104
	v_fma_f32 v104, v143, v107, v157
	v_exp_f32_e32 v138, v100
	v_fma_f32 v100, v143, v103, v157
	v_exp_f32_e32 v141, v96
	v_fma_f32 v96, v143, v98, v157
	v_exp_f32_e32 v131, v108
	v_exp_f32_e32 v135, v104
	v_exp_f32_e32 v139, v100
	v_exp_f32_e32 v142, v96
	v_fmac_f32_e32 v157, v143, v99
	v_sub_f32_e32 v96, v155, v127
	v_exp_f32_e32 v96, v96
	v_cmp_gt_f32_e32 vcc, v127, v155
	s_cbranch_vccnz .LBB0_70
	s_branch .LBB0_71

; template <int MODE>
; __device__ __forceinline__ void attn_pass(LAS unsigned char* lds, const bf16_t* base, int gk, int q0, const float* relb_b, const unsigned* selrow, f32x4 (&o)[2][4]) {
;     ...
;             if (fast) {
;                 float mx = fmaxf(fmaxf(s[qt][0][0], s[qt][0][1]), fmaxf(s[qt][0][2], s[qt][0][3]));
; #pragma unroll
;                 for (int nt = 1; nt < 4; ++nt) mx = fmaxf(mx, fmaxf(fmaxf(s[qt][nt][0], s[qt][nt][1]), fmaxf(s[qt][nt][2], s[qt][nt][3])));
;                 mx = fmaxf(mx, __shfl_xor(mx, 16)); mx = fmaxf(mx, __shfl_xor(mx, 32));
;                 const float mxl = selb ? (mx * C1 + bias_far) : -1e30f;
;                 mnew = fmaxf(mrun[qt], mxl); alpha = __builtin_amdgcn_exp2f(mrun[qt] - mnew);
;                 const float c1 = selb ? C1 : 0.f, c2 = selb ? (bias_far - mnew) : -1e30f;
; #pragma unroll
;                 for (int nt = 0; nt < 4; ++nt)
; #pragma unroll
;                     for (int j = 0; j < 4; ++j) s[qt][nt][j] = __builtin_amdgcn_exp2f(s[qt][nt][j] * c1 + c2);
.LBB0_194:
	v_max3_f32 v2, v175, v174, v173
	v_max3_f32 v2, v2, v172, v171
	v_max3_f32 v2, v2, v170, v169
	v_max3_f32 v2, v2, v168, v167
	v_max3_f32 v2, v2, v166, v165
	v_max3_f32 v2, v2, v164, v163
	v_max3_f32 v2, v2, v162, v161
	v_max_f32_e32 v2, v2, v160
	v_mov_b32_e32 v3, v2
	s_waitcnt lgkmcnt(0)
	s_nop 1
	v_permlane16_swap_b32_e32 v2, v3
	s_nop 0
	v_max_f32_e32 v2, v2, v3
	v_mov_b32_e32 v3, v2
	s_nop 1
	v_permlane32_swap_b32_e32 v2, v3
	s_nop 0
	v_max_f32_e32 v2, v2, v3
	v_fmamk_f32 v2, v2, 0x3e38aa3b, v188
	v_max_f32_e32 v3, v200, v200
	v_max_f32_e32 v3, v3, v2
	v_sub_f32_e32 v197, v188, v3
	v_fmamk_f32 v2, v172, 0x3e38aa3b, v197
	v_exp_f32_e32 v144, v2
	v_fmamk_f32 v2, v173, 0x3e38aa3b, v197
	v_exp_f32_e32 v145, v2
	v_fmamk_f32 v2, v174, 0x3e38aa3b, v197
	v_exp_f32_e32 v146, v2
	v_fmamk_f32 v2, v175, 0x3e38aa3b, v197
	v_exp_f32_e32 v147, v2
	v_fmamk_f32 v2, v168, 0x3e38aa3b, v197
	v_exp_f32_e32 v148, v2
	v_fmamk_f32 v2, v169, 0x3e38aa3b, v197
	v_exp_f32_e32 v149, v2
	v_fmamk_f32 v2, v170, 0x3e38aa3b, v197
	v_exp_f32_e32 v150, v2
	v_fmamk_f32 v2, v171, 0x3e38aa3b, v197
	v_exp_f32_e32 v151, v2
	v_fmamk_f32 v2, v164, 0x3e38aa3b, v197
	v_exp_f32_e32 v152, v2
	v_fmamk_f32 v2, v165, 0x3e38aa3b, v197
	v_exp_f32_e32 v153, v2
	v_fmamk_f32 v2, v166, 0x3e38aa3b, v197
	v_exp_f32_e32 v154, v2
	v_fmamk_f32 v2, v167, 0x3e38aa3b, v197
	v_exp_f32_e32 v155, v2
	v_fmamk_f32 v2, v160, 0x3e38aa3b, v197
	v_exp_f32_e32 v156, v2
	v_fmamk_f32 v2, v161, 0x3e38aa3b, v197
	v_exp_f32_e32 v157, v2
	v_fmamk_f32 v2, v162, 0x3e38aa3b, v197
	v_exp_f32_e32 v158, v2
	v_fmac_f32_e32 v197, 0x3e38aa3b, v163
	v_sub_f32_e32 v2, v200, v3
	v_exp_f32_e32 v2, v2
	v_cmp_gt_f32_e32 vcc, v3, v200
	s_cbranch_vccnz .LBB0_154
	s_branch .LBB0_155

; template <int MODE>
; __device__ __forceinline__ void attn_pass(LAS unsigned char* lds, const bf16_t* base, int gk, int q0, const float* relb_b, const unsigned* selrow, f32x4 (&o)[2][4]) {
;     ...
;             if (fast) {
;                 float mx = fmaxf(fmaxf(s[qt][0][0], s[qt][0][1]), fmaxf(s[qt][0][2], s[qt][0][3]));
; #pragma unroll
;                 for (int nt = 1; nt < 4; ++nt) mx = fmaxf(mx, fmaxf(fmaxf(s[qt][nt][0], s[qt][nt][1]), fmaxf(s[qt][nt][2], s[qt][nt][3])));
;                 mx = fmaxf(mx, __shfl_xor(mx, 16)); mx = fmaxf(mx, __shfl_xor(mx, 32));
;                 const float mxl = selb ? (mx * C1 + bias_far) : -1e30f;
;                 mnew = fmaxf(mrun[qt], mxl); alpha = __builtin_amdgcn_exp2f(mrun[qt] - mnew);
;                 const float c1 = selb ? C1 : 0.f, c2 = selb ? (bias_far - mnew) : -1e30f;
; #pragma unroll
;                 for (int nt = 0; nt < 4; ++nt)
; #pragma unroll
;                     for (int j = 0; j < 4; ++j) s[qt][nt][j] = __builtin_amdgcn_exp2f(s[qt][nt][j] * c1 + c2);
.LBB0_228:
	v_max3_f32 v159, v143, v142, v141
	v_max3_f32 v159, v159, v140, v139
	v_max3_f32 v159, v159, v138, v137
	v_max3_f32 v159, v159, v136, v135
	v_max3_f32 v159, v159, v134, v133
	v_max3_f32 v159, v159, v132, v131
	v_max3_f32 v159, v159, v130, v129
	v_max_f32_e32 v159, v159, v128
	v_mov_b32_e32 v160, v159
	s_waitcnt lgkmcnt(0)
	s_nop 1
	v_permlane16_swap_b32_e32 v159, v160
	s_nop 0
	v_max_f32_e32 v159, v159, v160
	v_mov_b32_e32 v160, v159
	s_nop 1
	v_permlane32_swap_b32_e32 v159, v160
	s_nop 0
	v_max_f32_e32 v159, v159, v160
	v_fmamk_f32 v159, v159, 0x3e38aa3b, v188
	v_max_f32_e32 v160, v196, v196
	v_max_f32_e32 v159, v160, v159
	v_sub_f32_e32 v200, v188, v159
	v_fmamk_f32 v140, v140, 0x3e38aa3b, v200
	v_fmamk_f32 v136, v136, 0x3e38aa3b, v200
	v_fmamk_f32 v132, v132, 0x3e38aa3b, v200
	v_exp_f32_e32 v160, v140
	v_fmamk_f32 v140, v141, 0x3e38aa3b, v200
	v_exp_f32_e32 v164, v136
	v_fmamk_f32 v136, v137, 0x3e38aa3b, v200
	v_exp_f32_e32 v168, v132
	v_fmamk_f32 v132, v133, 0x3e38aa3b, v200
	v_fmamk_f32 v128, v128, 0x3e38aa3b, v200
	v_exp_f32_e32 v161, v140
	v_fmamk_f32 v140, v142, 0x3e38aa3b, v200
	v_exp_f32_e32 v165, v136
	v_fmamk_f32 v136, v138, 0x3e38aa3b, v200
	v_exp_f32_e32 v169, v132
	v_fmamk_f32 v132, v134, 0x3e38aa3b, v200
	v_exp_f32_e32 v172, v128
	v_fmamk_f32 v128, v129, 0x3e38aa3b, v200
	v_exp_f32_e32 v162, v140
	v_fmamk_f32 v140, v143, 0x3e38aa3b, v200
	v_exp_f32_e32 v166, v136
	v_fmamk_f32 v136, v139, 0x3e38aa3b, v200
	v_exp_f32_e32 v170, v132
	v_fmamk_f32 v132, v135, 0x3e38aa3b, v200
	v_exp_f32_e32 v173, v128
	v_fmamk_f32 v128, v130, 0x3e38aa3b, v200
	v_exp_f32_e32 v163, v140
	v_exp_f32_e32 v167, v136
	v_exp_f32_e32 v171, v132
	v_exp_f32_e32 v174, v128
	v_fmac_f32_e32 v200, 0x3e38aa3b, v131
	v_sub_f32_e32 v128, v196, v159
	v_exp_f32_e32 v128, v128
	v_cmp_gt_f32_e32 vcc, v159, v196
	s_cbranch_vccnz .LBB0_158
	s_branch .LBB0_159
